# attention loop: K-frag ds_read prefetch 3 steps ahead, V tr-read groups one group ahead (extra regs v230-245), first PV group reads hoisted, no vmcnt drain in tile-B staging
# baseline (speedup 1.0000x reference)
; __device__ __forceinline__ void finishSM(f32x16& p0, f32x16& p1, float alpha, float& l_reg, bf16x8& pa0, bf16x8& pa1, bf16x8& pa2, bf16x8& pa3) {
;   for (int r = 0; r < 16; ++r) p1[r] = __builtin_amdgcn_exp2f(p1[r]);
;   float ps = 0; for (int r = 0; r < 16; ++r) ps += p0[r]; for (int r = 0; r < 16; ++r) ps += p1[r];
;   { auto rr = __builtin_amdgcn_permlane32_swap(__float_as_uint(ps), __float_as_uint(ps), false, false);
;     ps = __uint_as_float(rr[0]) + __uint_as_float(rr[1]); }
;   l_reg = l_reg * alpha + ps;
;     ...
;   PK4(p0, 0, pa0); PK4(p0, 8, pa1); PK4(p1, 0, pa2); PK4(p1, 8, pa3);
;     ...
; }
; __device__ __forceinline__ void qkt(f32x16& p0, f32x16& p1, const bf16* Ks, const bf16x8* qr, int r32, int hi) {
;   p0 = f32x16{}; p1 = f32x16{};
;   for (int d0 = 0; d0 < 8; ++d0) { int cb = (d0 * 16 + hi * 8) * 2;
;     bf16x8 b0 = *reinterpret_cast<const bf16x8*>((const char*)Ks + KSWZ(r32, cb));
;     bf16x8 b1 = *reinterpret_cast<const bf16x8*>((const char*)Ks + KSWZ(32 + r32, cb));
;     p0 = __builtin_amdgcn_mfma_f32_32x32x16_bf16(b0, qr[d0], p0, 0, 0, 0);
;     p1 = __builtin_amdgcn_mfma_f32_32x32x16_bf16(b1, qr[d0], p1, 0, 0, 0); }
; }
; __device__ __forceinline__ int v_st(int k, int c) { const int kk = (k & ~0xC) | ((k & 4) << 1) | ((k & 8) >> 1); return ((kk >> 3) * 4 + (c >> 5)) * 512 + ((kk & 7) * 32 + (c & 31)) * 2; }
; __device__ __forceinline__ int v_rd_base(int lane) { return ((lane & 3) << 3) | (((lane >> 2) & 3) << 6) | (((lane >> 4) & 1) << 5) | (((lane >> 5) & 1) << 8); }
; template <int OFF> __device__ __forceinline__ s16x4 tr_read(int vb) {
;   s16x4 r; asm volatile("ds_read_b64_tr_b16 %0, %1 offset:%2" : "=&v"(r) : "v"(vb), "i"(OFF) : "memory"); return r;
; }
; template <int D0> __device__ __forceinline__ void pv_one(f32x16& od, int vb, bf16x8 pa0, bf16x8 pa1, bf16x8 pa2, bf16x8 pa3) {
;   const s16x4 l0 = tr_read<v_rd_off(D0, 0, 0)>(vb), h0 = tr_read<v_rd_off(D0, 0, 1)>(vb), l1 = tr_read<v_rd_off(D0, 1, 0)>(vb), h1 = tr_read<v_rd_off(D0, 1, 1)>(vb);
;   const s16x4 l2 = tr_read<v_rd_off(D0, 2, 0)>(vb), h2 = tr_read<v_rd_off(D0, 2, 1)>(vb), l3 = tr_read<v_rd_off(D0, 3, 0)>(vb), h3 = tr_read<v_rd_off(D0, 3, 1)>(vb);
.LBB0_1529:
	ds_read_b128 v[64:67], v192 offset:49152
	ds_read_b128 v[68:71], v192 offset:57344
	ds_read_b128 v[208:211], v199 offset:49152
	ds_read_b128 v[212:215], v199 offset:57344
	ds_read_b128 v[230:233], v198 offset:49152
	ds_read_b128 v[234:237], v198 offset:57344
	ds_read_b128 v[238:241], v195 offset:49152
	ds_read_b128 v[242:245], v195 offset:57344
	v_add_f32_e32 v160, 0, v161
	v_add_f32_e32 v160, v162, v160
	s_waitcnt lgkmcnt(7)
	v_mfma_f32_32x32x16_bf16 v[80:95], v[64:67], v[120:123], 0
	v_add_f32_e32 v160, v174, v160
	v_add_f32_e32 v160, v175, v160
	v_add_f32_e32 v160, v204, v160
	v_add_f32_e32 v160, v207, v160
	v_add_f32_e32 v160, v163, v160
	v_add_f32_e32 v160, v173, v160
	v_add_f32_e32 v160, v168, v160
	s_waitcnt lgkmcnt(6)
	v_mfma_f32_32x32x16_bf16 v[64:79], v[68:71], v[120:123], 0
	v_add_f32_e32 v160, v170, v160
	v_add_f32_e32 v160, v171, v160
	v_add_f32_e32 v160, v172, v160
	v_exp_f32_e32 v156, v156
	v_add_f32_e32 v160, v165, v160
	v_exp_f32_e32 v157, v157
	v_add_f32_e32 v160, v166, v160
	s_waitcnt lgkmcnt(5)
	v_mfma_f32_32x32x16_bf16 v[80:95], v[208:211], v[112:115], v[80:95]
	v_exp_f32_e32 v154, v154
	v_add_f32_e32 v160, v167, v160
	v_exp_f32_e32 v155, v155
	v_add_f32_e32 v160, v169, v160
	v_exp_f32_e32 v148, v148
	v_add_f32_e32 v160, v156, v160
	v_exp_f32_e32 v149, v149
	s_waitcnt lgkmcnt(4)
	v_mfma_f32_32x32x16_bf16 v[64:79], v[212:215], v[112:115], v[64:79]
	ds_read_b128 v[208:211], v194 offset:49152
	ds_read_b128 v[212:215], v194 offset:57344
	v_add_f32_e32 v160, v157, v160
	v_exp_f32_e32 v146, v146
	v_add_f32_e32 v160, v154, v160
	v_exp_f32_e32 v147, v147
	v_add_f32_e32 v160, v155, v160
	v_exp_f32_e32 v144, v144
	s_waitcnt lgkmcnt(5)
	v_mfma_f32_32x32x16_bf16 v[80:95], v[230:233], v[124:127], v[80:95]
	v_add_f32_e32 v160, v148, v160
	v_exp_f32_e32 v145, v145
	v_add_f32_e32 v160, v149, v160
	v_exp_f32_e32 v158, v158
	v_add_f32_e32 v160, v146, v160
	v_exp_f32_e32 v159, v159
	v_add_f32_e32 v160, v147, v160
	s_waitcnt lgkmcnt(4)
	v_mfma_f32_32x32x16_bf16 v[64:79], v[234:237], v[124:127], v[64:79]
	ds_read_b128 v[230:233], v193 offset:49152
	ds_read_b128 v[234:237], v193 offset:57344
	v_exp_f32_e32 v152, v152
	v_add_f32_e32 v160, v144, v160
	v_exp_f32_e32 v153, v153
	v_add_f32_e32 v160, v145, v160
	v_exp_f32_e32 v150, v150
	v_add_f32_e32 v160, v158, v160
	s_waitcnt lgkmcnt(5)
	v_mfma_f32_32x32x16_bf16 v[80:95], v[238:241], v[116:119], v[80:95]
	v_exp_f32_e32 v151, v151
	v_add_f32_e32 v160, v159, v160
	v_add_f32_e32 v160, v152, v160
	v_add_f32_e32 v160, v153, v160
	v_add_f32_e32 v160, v150, v160
	v_add_f32_e32 v201, v151, v160
	v_mov_b32_e32 v202, v201
	s_waitcnt lgkmcnt(4)
	v_mfma_f32_32x32x16_bf16 v[64:79], v[242:245], v[116:119], v[64:79]
	ds_read_b128 v[238:241], v196 offset:49152
	ds_read_b128 v[242:245], v196 offset:57344
	v_cvt_pk_bf16_f32 v160, v161, v162
	v_cvt_pk_bf16_f32 v162, v204, v207
	v_permlane32_swap_b32_e32 v201, v202
	v_cvt_pk_bf16_f32 v161, v174, v175
	v_cvt_pk_bf16_f32 v163, v163, v173
	s_waitcnt lgkmcnt(5)
	v_mfma_f32_32x32x16_bf16 v[80:95], v[208:211], v[108:111], v[80:95]
	v_permlane32_swap_b32_e32 v160, v162
	v_cvt_pk_bf16_f32 v170, v168, v170
	v_cvt_pk_bf16_f32 v171, v171, v172
	v_cvt_pk_bf16_f32 v172, v165, v166
	v_cvt_pk_bf16_f32 v173, v167, v169
	v_cvt_pk_bf16_f32 v166, v156, v157
	s_waitcnt lgkmcnt(4)
	v_mfma_f32_32x32x16_bf16 v[64:79], v[212:215], v[108:111], v[64:79]
	ds_read_b128 v[208:211], v197 offset:49152
	ds_read_b128 v[212:215], v197 offset:57344
	v_cvt_pk_bf16_f32 v167, v154, v155
	v_cvt_pk_bf16_f32 v168, v148, v149
	v_cvt_pk_bf16_f32 v169, v146, v147
	v_cvt_pk_bf16_f32 v204, v144, v145
	v_cvt_pk_bf16_f32 v205, v158, v159
	v_cvt_pk_bf16_f32 v206, v152, v153
	s_waitcnt lgkmcnt(5)
	v_mfma_f32_32x32x16_bf16 v[80:95], v[230:233], v[104:107], v[80:95]
	v_cvt_pk_bf16_f32 v207, v150, v151
	v_permlane32_swap_b32_e32 v161, v163
	v_permlane32_swap_b32_e32 v170, v172
	v_permlane32_swap_b32_e32 v171, v173
	s_waitcnt lgkmcnt(4)
	v_mfma_f32_32x32x16_bf16 v[64:79], v[234:237], v[104:107], v[64:79]
	v_permlane32_swap_b32_e32 v166, v168
	v_permlane32_swap_b32_e32 v167, v169
	v_permlane32_swap_b32_e32 v204, v206
	s_waitcnt lgkmcnt(3)
	v_mfma_f32_32x32x16_bf16 v[80:95], v[238:241], v[100:103], v[80:95]
	v_permlane32_swap_b32_e32 v205, v207
	s_waitcnt lgkmcnt(2)
	v_mfma_f32_32x32x16_bf16 v[64:79], v[242:245], v[100:103], v[64:79]
	s_waitcnt lgkmcnt(1)
	v_mfma_f32_32x32x16_bf16 v[80:95], v[208:211], v[96:99], v[80:95]
	s_waitcnt lgkmcnt(0)
	v_mfma_f32_32x32x16_bf16 v[64:79], v[212:215], v[96:99], v[64:79]
	ds_read_b64_tr_b16 v[208:209], v187 offset:0
	ds_read_b64_tr_b16 v[210:211], v187 offset:2048
	ds_read_b64_tr_b16 v[212:213], v187 offset:4096
	ds_read_b64_tr_b16 v[214:215], v187 offset:6144
	ds_read_b64_tr_b16 v[218:219], v187 offset:8192
	ds_read_b64_tr_b16 v[220:221], v187 offset:10240
	ds_read_b64_tr_b16 v[222:223], v187 offset:12288
	ds_read_b64_tr_b16 v[224:225], v187 offset:14336
	s_movk_i32 s4, 0xa000
	v_add_co_u32_e32 v144, vcc, s4, v178
	s_movk_i32 s4, 0xc000
	s_nop 0
	v_addc_co_u32_e32 v145, vcc, -1, v179, vcc
	v_add_co_u32_e32 v148, vcc, s4, v178
	s_mov_b32 s4, 0xe53fa000
	s_nop 0
	v_addc_co_u32_e32 v149, vcc, -1, v179, vcc
	v_add_co_u32_e32 v152, vcc, s4, v178
	s_mov_b32 s4, 0xe53fc000
	s_nop 0
	v_addc_co_u32_e32 v153, vcc, -1, v179, vcc
	v_add_co_u32_e32 v156, vcc, s4, v178
	global_load_dwordx4 v[144:147], v[144:145], off
	s_nop 0
	global_load_dwordx4 v[148:151], v[148:149], off
	v_addc_co_u32_e32 v157, vcc, -1, v179, vcc
	global_load_dwordx4 v[152:155], v[152:153], off
	s_nop 0
	global_load_dwordx4 v[156:159], v[156:157], off
	s_waitcnt lgkmcnt(7)
; #define SBAR() __builtin_amdgcn_sched_barrier(0)
; __device__ __forceinline__ void partialSM(f32x16& p0, f32x16& p1, float& m_reg, float& mn, float& alpha) {
;   constexpr float C = SCALE * 1.4426950408889634f;
;   float pmax = p0[0]; for (int r = 1; r < 16; ++r) pmax = fmaxf(pmax, p0[r]); for (int r = 0; r < 16; ++r) pmax = fmaxf(pmax, p1[r]);
;   { auto rr = __builtin_amdgcn_permlane32_swap(__float_as_uint(pmax), __float_as_uint(pmax), false, false);
;     pmax = fmaxf(__uint_as_float(rr[0]), __uint_as_float(rr[1])); }
;   if (__builtin_expect(__all(pmax - m_reg <= THR / SCALE), 1)) { mn = m_reg; alpha = 1.f; }
;   else { mn = fmaxf(m_reg, pmax); alpha = __builtin_amdgcn_exp2f((m_reg - mn) * C); m_reg = mn; }
; template <int OFF> __device__ __forceinline__ s16x4 tr_read(int vb) {
;   s16x4 r; asm volatile("ds_read_b64_tr_b16 %0, %1 offset:%2" : "=&v"(r) : "v"(vb), "i"(OFF) : "memory"); return r;
; }
; template <int D0> __device__ __forceinline__ void pv_one(f32x16& od, int vb, bf16x8 pa0, bf16x8 pa1, bf16x8 pa2, bf16x8 pa3) {
;   const s16x4 l0 = tr_read<v_rd_off(D0, 0, 0)>(vb), h0 = tr_read<v_rd_off(D0, 0, 1)>(vb), l1 = tr_read<v_rd_off(D0, 1, 0)>(vb), h1 = tr_read<v_rd_off(D0, 1, 1)>(vb);
;   const s16x4 l2 = tr_read<v_rd_off(D0, 2, 0)>(vb), h2 = tr_read<v_rd_off(D0, 2, 1)>(vb), l3 = tr_read<v_rd_off(D0, 3, 0)>(vb), h3 = tr_read<v_rd_off(D0, 3, 1)>(vb);
;   asm volatile("s_waitcnt lgkmcnt(0)" ::: "memory"); SBAR();
;     ...
;   od = __builtin_amdgcn_mfma_f32_32x32x16_bf16(pa0, PK(l0, h0), od, 0, 0, 0);
;   od = __builtin_amdgcn_mfma_f32_32x32x16_bf16(pa1, PK(l1, h1), od, 0, 0, 0);
;   od = __builtin_amdgcn_mfma_f32_32x32x16_bf16(pa2, PK(l2, h2), od, 0, 0, 0);
;   od = __builtin_amdgcn_mfma_f32_32x32x16_bf16(pa3, PK(l3, h3), od, 0, 0, 0);
;     ...
; }
; __device__ __forceinline__ void pv_d0(f32x16* o, int vb, bf16x8 pa0, bf16x8 pa1, bf16x8 pa2, bf16x8 pa3) {
;   pv_one<0>(o[0], vb, pa0, pa1, pa2, pa3); pv_one<1>(o[1], vb, pa0, pa1, pa2, pa3); pv_one<2>(o[2], vb, pa0, pa1, pa2, pa3); pv_one<3>(o[3], vb, pa0, pa1, pa2, pa3);
	ds_read_b64_tr_b16 v[230:231], v187 offset:512
	ds_read_b64_tr_b16 v[232:233], v187 offset:2560
	ds_read_b64_tr_b16 v[234:235], v187 offset:4608
	ds_read_b64_tr_b16 v[236:237], v187 offset:6656
	ds_read_b64_tr_b16 v[238:239], v187 offset:8704
	ds_read_b64_tr_b16 v[240:241], v187 offset:10752
	ds_read_b64_tr_b16 v[242:243], v187 offset:12800
	ds_read_b64_tr_b16 v[244:245], v187 offset:14848
	s_waitcnt lgkmcnt(8)
	s_nop 0
	v_mfma_f32_32x32x16_bf16 v[0:15], v[160:163], v[208:211], v[0:15]
	ds_read_b64_tr_b16 v[208:209], v187 offset:1024
	ds_read_b64_tr_b16 v[210:211], v187 offset:3072
	v_mfma_f32_32x32x16_bf16 v[0:15], v[170:173], v[212:215], v[0:15]
	ds_read_b64_tr_b16 v[212:213], v187 offset:5120
	ds_read_b64_tr_b16 v[214:215], v187 offset:7168
	v_mfma_f32_32x32x16_bf16 v[0:15], v[166:169], v[218:221], v[0:15]
	ds_read_b64_tr_b16 v[218:219], v187 offset:9216
	ds_read_b64_tr_b16 v[220:221], v187 offset:11264
	v_mfma_f32_32x32x16_bf16 v[0:15], v[204:207], v[222:225], v[0:15]
	s_waitcnt lgkmcnt(13)
	ds_read_b64_tr_b16 v[222:223], v187 offset:13312
	ds_read_b64_tr_b16 v[224:225], v187 offset:15360
	s_waitcnt lgkmcnt(8)
	v_mfma_f32_32x32x16_bf16 v[48:63], v[160:163], v[230:233], v[48:63]
	ds_read_b64_tr_b16 v[230:231], v187 offset:1536
	ds_read_b64_tr_b16 v[232:233], v187 offset:3584
	v_mfma_f32_32x32x16_bf16 v[48:63], v[170:173], v[234:237], v[48:63]
	ds_read_b64_tr_b16 v[234:235], v187 offset:5632
	ds_read_b64_tr_b16 v[236:237], v187 offset:7680
	v_mfma_f32_32x32x16_bf16 v[48:63], v[166:169], v[238:241], v[48:63]
	ds_read_b64_tr_b16 v[238:239], v187 offset:9728
	ds_read_b64_tr_b16 v[240:241], v187 offset:11776
	v_mfma_f32_32x32x16_bf16 v[48:63], v[204:207], v[242:245], v[48:63]
	s_waitcnt lgkmcnt(13)
	ds_read_b64_tr_b16 v[242:243], v187 offset:13824
	ds_read_b64_tr_b16 v[244:245], v187 offset:15872
	s_waitcnt lgkmcnt(8)
	v_mfma_f32_32x32x16_bf16 v[32:47], v[160:163], v[208:211], v[32:47]
	v_mfma_f32_32x32x16_bf16 v[32:47], v[170:173], v[212:215], v[32:47]
	v_mfma_f32_32x32x16_bf16 v[32:47], v[166:169], v[218:221], v[32:47]
	v_mfma_f32_32x32x16_bf16 v[32:47], v[204:207], v[222:225], v[32:47]
	s_waitcnt lgkmcnt(0)
	v_mfma_f32_32x32x16_bf16 v[16:31], v[160:163], v[230:233], v[16:31]
	v_max_f32_e32 v160, v81, v81
	v_max_f32_e32 v161, v80, v80
	v_max_f32_e32 v160, v161, v160
	v_max3_f32 v160, v160, v82, v83
	v_max3_f32 v160, v160, v84, v85
	v_max3_f32 v160, v160, v86, v87
	v_max3_f32 v160, v160, v88, v89
	v_max3_f32 v160, v160, v90, v91
	v_max3_f32 v160, v160, v92, v93
	v_mfma_f32_32x32x16_bf16 v[16:31], v[170:173], v[234:237], v[16:31]
	v_max3_f32 v160, v160, v94, v95
	v_max3_f32 v160, v160, v64, v65
	v_max3_f32 v160, v160, v66, v67
	v_max3_f32 v160, v160, v68, v69
	v_max3_f32 v160, v160, v70, v71
	v_max3_f32 v160, v160, v72, v73
	v_max3_f32 v160, v160, v74, v75
	v_max3_f32 v160, v160, v76, v77
	v_mfma_f32_32x32x16_bf16 v[16:31], v[166:169], v[238:241], v[16:31]
	v_max3_f32 v160, v160, v78, v79
	v_mov_b32_e32 v161, v160
	s_nop 1
	v_permlane32_swap_b32_e32 v160, v161
	v_max_f32_e32 v161, v161, v161
	v_max_f32_e32 v160, v160, v160
	v_max_f32_e32 v160, v160, v161
	v_sub_f32_e32 v161, v160, v164
	v_cmp_ge_f32_e32 vcc, s14, v161
	v_max_f32_e32 v161, v164, v164
	v_max_f32_e32 v160, v161, v160
	v_mfma_f32_32x32x16_bf16 v[16:31], v[204:207], v[242:245], v[16:31]
	v_sub_f32_e32 v161, v164, v160
	v_mul_f32_e32 v161, 0x3e0293ee, v161
	v_exp_f32_e32 v161, v161
	s_cmp_eq_u64 vcc, exec
	s_cselect_b64 s[38:39], -1, 0
	s_barrier
	s_waitcnt vmcnt(4)
	v_cndmask_b32_e64 v203, v161, 1.0, s[38:39]
	v_cmp_gt_f32_e32 vcc, 1.0, v203
	s_waitcnt vmcnt(7)
	ds_write_b128 v188, v[128:131]
	s_waitcnt vmcnt(6)
	ds_write_b128 v189, v[136:139]
	s_waitcnt vmcnt(5)
	ds_write_b128 v190, v[132:135] offset:32768
	s_waitcnt vmcnt(4)
	ds_write_b128 v191, v[140:143] offset:32768
	s_cbranch_vccz .LBB0_1533
	s_and_saveexec_b64 s[4:5], s[36:37]
	ds_write_b32 v184, v203 offset:128
	s_or_b64 exec, exec, s[4:5]
	s_waitcnt lgkmcnt(0)
	v_add_u32_e32 v161, s8, v176
	ds_read_b128 v[166:169], v161 offset:224
	ds_read_b128 v[170:173], v161 offset:192
	ds_read_b128 v[204:207], v161 offset:160
	ds_read_b128 v[208:211], v161 offset:128
	s_waitcnt lgkmcnt(3)
	v_pk_mul_f32 v[12:13], v[12:13], v[166:167]
	s_waitcnt lgkmcnt(2)
	v_pk_mul_f32 v[8:9], v[8:9], v[170:171]
	s_waitcnt lgkmcnt(1)
	v_pk_mul_f32 v[4:5], v[4:5], v[204:205]
	v_pk_mul_f32 v[14:15], v[14:15], v[168:169]
	v_pk_mul_f32 v[10:11], v[10:11], v[172:173]
	v_pk_mul_f32 v[6:7], v[6:7], v[206:207]
	s_waitcnt lgkmcnt(0)
	v_pk_mul_f32 v[2:3], v[2:3], v[210:211]
	v_pk_mul_f32 v[0:1], v[0:1], v[208:209]
	v_pk_mul_f32 v[60:61], v[60:61], v[166:167]
	v_pk_mul_f32 v[56:57], v[56:57], v[170:171]
	v_pk_mul_f32 v[52:53], v[52:53], v[204:205]
	v_pk_mul_f32 v[62:63], v[62:63], v[168:169]
	v_pk_mul_f32 v[58:59], v[58:59], v[172:173]
	v_pk_mul_f32 v[54:55], v[54:55], v[206:207]
	v_pk_mul_f32 v[50:51], v[50:51], v[210:211]
	v_pk_mul_f32 v[48:49], v[48:49], v[208:209]
	v_pk_mul_f32 v[44:45], v[44:45], v[166:167]
	v_pk_mul_f32 v[40:41], v[40:41], v[170:171]
	v_pk_mul_f32 v[36:37], v[36:37], v[204:205]
	v_pk_mul_f32 v[46:47], v[46:47], v[168:169]
	v_pk_mul_f32 v[42:43], v[42:43], v[172:173]
	v_pk_mul_f32 v[38:39], v[38:39], v[206:207]
	v_pk_mul_f32 v[34:35], v[34:35], v[210:211]
	v_pk_mul_f32 v[32:33], v[32:33], v[208:209]
	v_pk_mul_f32 v[28:29], v[28:29], v[166:167]
	v_pk_mul_f32 v[24:25], v[24:25], v[170:171]
	v_pk_mul_f32 v[20:21], v[20:21], v[204:205]
	v_pk_mul_f32 v[30:31], v[30:31], v[168:169]
	v_pk_mul_f32 v[26:27], v[26:27], v[172:173]
	v_pk_mul_f32 v[22:23], v[22:23], v[206:207]
	v_pk_mul_f32 v[18:19], v[18:19], v[210:211]
	v_pk_mul_f32 v[16:17], v[16:17], v[208:209]
; __device__ __forceinline__ void partialSM(f32x16& p0, f32x16& p1, float& m_reg, float& mn, float& alpha) {
;   constexpr float C = SCALE * 1.4426950408889634f;
;   float pmax = p0[0]; for (int r = 1; r < 16; ++r) pmax = fmaxf(pmax, p0[r]); for (int r = 0; r < 16; ++r) pmax = fmaxf(pmax, p1[r]);
;   { auto rr = __builtin_amdgcn_permlane32_swap(__float_as_uint(pmax), __float_as_uint(pmax), false, false);
;     pmax = fmaxf(__uint_as_float(rr[0]), __uint_as_float(rr[1])); }
;   if (__builtin_expect(__all(pmax - m_reg <= THR / SCALE), 1)) { mn = m_reg; alpha = 1.f; }
;   else { mn = fmaxf(m_reg, pmax); alpha = __builtin_amdgcn_exp2f((m_reg - mn) * C); m_reg = mn; }
;   float mnC = -mn * C;
;   for (int r = 0; r < 16; ++r) p0[r] = fmaf(p0[r], C, mnC); for (int r = 0; r < 16; ++r) p1[r] = fmaf(p1[r], C, mnC);
;   for (int r = 0; r < 16; ++r) p0[r] = __builtin_amdgcn_exp2f(p0[r]);
; }
; __device__ __forceinline__ void finishSM(f32x16& p0, f32x16& p1, float alpha, float& l_reg, bf16x8& pa0, bf16x8& pa1, bf16x8& pa2, bf16x8& pa3) {
;   for (int r = 0; r < 16; ++r) p1[r] = __builtin_amdgcn_exp2f(p1[r]);
;   float ps = 0; for (int r = 0; r < 16; ++r) ps += p0[r]; for (int r = 0; r < 16; ++r) ps += p1[r];
;   { auto rr = __builtin_amdgcn_permlane32_swap(__float_as_uint(ps), __float_as_uint(ps), false, false);
;     ps = __uint_as_float(rr[0]) + __uint_as_float(rr[1]); }
;   l_reg = l_reg * alpha + ps;
;     ...
;   PK4(p0, 0, pa0); PK4(p0, 8, pa1); PK4(p1, 0, pa2); PK4(p1, 8, pa3);
;     ...
; }
; __device__ __forceinline__ void qkt(f32x16& p0, f32x16& p1, const bf16* Ks, const bf16x8* qr, int r32, int hi) {
;   p0 = f32x16{}; p1 = f32x16{};
;   for (int d0 = 0; d0 < 8; ++d0) { int cb = (d0 * 16 + hi * 8) * 2;
;     bf16x8 b0 = *reinterpret_cast<const bf16x8*>((const char*)Ks + KSWZ(r32, cb));
;     bf16x8 b1 = *reinterpret_cast<const bf16x8*>((const char*)Ks + KSWZ(32 + r32, cb));
;     p0 = __builtin_amdgcn_mfma_f32_32x32x16_bf16(b0, qr[d0], p0, 0, 0, 0);
;     p1 = __builtin_amdgcn_mfma_f32_32x32x16_bf16(b1, qr[d0], p1, 0, 0, 0); }
; }
.LBB0_1533:
	v_cndmask_b32_e64 v204, v160, v164, s[38:39]
	v_mul_f32_e32 v205, 0xbe0293ee, v204
	v_fmamk_f32 v80, v80, 0x3e0293ee, v205
	v_fmamk_f32 v81, v81, 0x3e0293ee, v205
	v_fmamk_f32 v82, v82, 0x3e0293ee, v205
	v_fmamk_f32 v83, v83, 0x3e0293ee, v205
	v_fmamk_f32 v84, v84, 0x3e0293ee, v205
	v_fmamk_f32 v85, v85, 0x3e0293ee, v205
	v_fmamk_f32 v86, v86, 0x3e0293ee, v205
	v_fmamk_f32 v87, v87, 0x3e0293ee, v205
	v_fmamk_f32 v88, v88, 0x3e0293ee, v205
	v_fmamk_f32 v89, v89, 0x3e0293ee, v205
	v_fmamk_f32 v90, v90, 0x3e0293ee, v205
	v_fmamk_f32 v91, v91, 0x3e0293ee, v205
	v_fmamk_f32 v92, v92, 0x3e0293ee, v205
	v_fmamk_f32 v93, v93, 0x3e0293ee, v205
	v_fmamk_f32 v94, v94, 0x3e0293ee, v205
	v_fmamk_f32 v95, v95, 0x3e0293ee, v205
	v_exp_f32_e32 v160, v80
	v_exp_f32_e32 v161, v81
	v_exp_f32_e32 v162, v82
	v_exp_f32_e32 v173, v83
	v_exp_f32_e32 v174, v84
	v_exp_f32_e32 v175, v85
	v_exp_f32_e32 v163, v86
	v_exp_f32_e32 v172, v87
	v_exp_f32_e32 v164, v88
	v_exp_f32_e32 v165, v89
	v_exp_f32_e32 v170, v90
	v_exp_f32_e32 v171, v91
	v_exp_f32_e32 v166, v92
	v_exp_f32_e32 v167, v93
	v_exp_f32_e32 v168, v94
	v_exp_f32_e32 v169, v95
	v_fmamk_f32 v214, v64, 0x3e0293ee, v205
	v_fmamk_f32 v215, v65, 0x3e0293ee, v205
	v_fmamk_f32 v217, v66, 0x3e0293ee, v205
	v_fmamk_f32 v218, v67, 0x3e0293ee, v205
	v_fmamk_f32 v219, v68, 0x3e0293ee, v205
	v_fmamk_f32 v207, v69, 0x3e0293ee, v205
	v_fmamk_f32 v208, v70, 0x3e0293ee, v205
	v_fmamk_f32 v209, v71, 0x3e0293ee, v205
	v_fmamk_f32 v210, v72, 0x3e0293ee, v205
	v_fmamk_f32 v211, v73, 0x3e0293ee, v205
	v_fmamk_f32 v212, v74, 0x3e0293ee, v205
	v_fmamk_f32 v213, v75, 0x3e0293ee, v205
	v_fmamk_f32 v206, v76, 0x3e0293ee, v205
	v_fmamk_f32 v220, v77, 0x3e0293ee, v205
	v_fmamk_f32 v221, v78, 0x3e0293ee, v205
	v_fmac_f32_e32 v205, 0x3e0293ee, v79
	s_waitcnt lgkmcnt(0)
	s_barrier
	ds_read_b128 v[64:67], v192 offset:32768
	ds_read_b128 v[68:71], v192 offset:40960
	ds_read_b128 v[222:225], v199 offset:32768
	ds_read_b128 v[226:229], v199 offset:40960
	ds_read_b128 v[230:233], v198 offset:32768
	ds_read_b128 v[234:237], v198 offset:40960
	ds_read_b128 v[238:241], v195 offset:32768
	ds_read_b128 v[242:245], v195 offset:40960
	v_exp_f32_e32 v214, v214
	v_exp_f32_e32 v215, v215
	s_waitcnt lgkmcnt(7)
	v_mfma_f32_32x32x16_bf16 v[80:95], v[64:67], v[120:123], 0
	v_exp_f32_e32 v217, v217
	v_exp_f32_e32 v218, v218
	v_exp_f32_e32 v219, v219
	v_exp_f32_e32 v207, v207
	v_exp_f32_e32 v208, v208
	v_exp_f32_e32 v209, v209
	v_exp_f32_e32 v210, v210
	s_waitcnt lgkmcnt(6)
	v_mfma_f32_32x32x16_bf16 v[64:79], v[68:71], v[120:123], 0
	v_exp_f32_e32 v211, v211
	v_exp_f32_e32 v212, v212
	v_exp_f32_e32 v213, v213
	v_exp_f32_e32 v220, v220
	v_exp_f32_e32 v221, v221
	s_waitcnt lgkmcnt(5)
	v_mfma_f32_32x32x16_bf16 v[80:95], v[222:225], v[112:115], v[80:95]
	s_waitcnt lgkmcnt(4)
	v_mfma_f32_32x32x16_bf16 v[64:79], v[226:229], v[112:115], v[64:79]
	ds_read_b128 v[222:225], v194 offset:32768
	ds_read_b128 v[226:229], v194 offset:40960
	s_waitcnt lgkmcnt(5)
	v_mfma_f32_32x32x16_bf16 v[80:95], v[230:233], v[124:127], v[80:95]
	s_waitcnt lgkmcnt(4)
	v_mfma_f32_32x32x16_bf16 v[64:79], v[234:237], v[124:127], v[64:79]
	ds_read_b128 v[230:233], v193 offset:32768
	ds_read_b128 v[234:237], v193 offset:40960
	s_waitcnt lgkmcnt(5)
	v_mfma_f32_32x32x16_bf16 v[80:95], v[238:241], v[116:119], v[80:95]
	s_waitcnt lgkmcnt(4)
	v_mfma_f32_32x32x16_bf16 v[64:79], v[242:245], v[116:119], v[64:79]
	ds_read_b128 v[238:241], v196 offset:32768
	ds_read_b128 v[242:245], v196 offset:40960
	s_waitcnt lgkmcnt(5)
	v_mfma_f32_32x32x16_bf16 v[80:95], v[222:225], v[108:111], v[80:95]
	s_waitcnt lgkmcnt(4)
	v_mfma_f32_32x32x16_bf16 v[64:79], v[226:229], v[108:111], v[64:79]
	ds_read_b128 v[222:225], v197 offset:32768
	ds_read_b128 v[226:229], v197 offset:40960
	s_waitcnt lgkmcnt(5)
	v_mfma_f32_32x32x16_bf16 v[80:95], v[230:233], v[104:107], v[80:95]
	s_waitcnt lgkmcnt(4)
	v_mfma_f32_32x32x16_bf16 v[64:79], v[234:237], v[104:107], v[64:79]
	s_waitcnt lgkmcnt(3)
	v_mfma_f32_32x32x16_bf16 v[80:95], v[238:241], v[100:103], v[80:95]
	s_waitcnt lgkmcnt(2)
	v_mfma_f32_32x32x16_bf16 v[64:79], v[242:245], v[100:103], v[64:79]
	s_waitcnt lgkmcnt(1)
	v_mfma_f32_32x32x16_bf16 v[80:95], v[222:225], v[96:99], v[80:95]
	v_exp_f32_e32 v223, v205
	v_add_f32_e32 v205, 0, v160
	v_add_f32_e32 v205, v161, v205
	v_add_f32_e32 v205, v162, v205
	v_add_f32_e32 v205, v173, v205
	v_add_f32_e32 v205, v174, v205
	v_add_f32_e32 v205, v175, v205
	v_add_f32_e32 v205, v163, v205
	v_add_f32_e32 v205, v172, v205
	v_add_f32_e32 v205, v164, v205
	v_add_f32_e32 v205, v165, v205
	v_add_f32_e32 v205, v170, v205
	v_add_f32_e32 v205, v171, v205
	v_add_f32_e32 v205, v166, v205
	v_add_f32_e32 v205, v167, v205
	v_add_f32_e32 v205, v168, v205
	v_add_f32_e32 v205, v169, v205
	v_add_f32_e32 v205, v214, v205
	v_add_f32_e32 v205, v215, v205
	v_add_f32_e32 v205, v217, v205
	v_add_f32_e32 v205, v218, v205
	v_add_f32_e32 v205, v219, v205
	v_add_f32_e32 v205, v207, v205
	v_add_f32_e32 v205, v208, v205
	v_add_f32_e32 v205, v209, v205
	v_exp_f32_e32 v222, v206
	v_add_f32_e32 v205, v210, v205
	v_add_f32_e32 v205, v211, v205
	s_waitcnt lgkmcnt(0)
	v_mfma_f32_32x32x16_bf16 v[64:79], v[226:229], v[96:99], v[64:79]
	v_add_f32_e32 v205, v212, v205
	v_add_f32_e32 v205, v213, v205
	v_add_f32_e32 v205, v222, v205
	v_add_f32_e32 v205, v220, v205
	v_add_f32_e32 v205, v221, v205
	v_add_f32_e32 v205, v223, v205
	v_mov_b32_e32 v206, v205
	v_cvt_pk_bf16_f32 v160, v160, v161
	v_cvt_pk_bf16_f32 v161, v162, v173
	v_cvt_pk_bf16_f32 v162, v174, v175
	v_cvt_pk_bf16_f32 v163, v163, v172
	v_cvt_pk_bf16_f32 v164, v164, v165
	v_cvt_pk_bf16_f32 v165, v170, v171
	v_cvt_pk_bf16_f32 v166, v166, v167
	v_cvt_pk_bf16_f32 v167, v168, v169
	v_cvt_pk_bf16_f32 v168, v214, v215
	v_cvt_pk_bf16_f32 v169, v217, v218
	v_cvt_pk_bf16_f32 v170, v219, v207
	v_cvt_pk_bf16_f32 v171, v208, v209
	v_cvt_pk_bf16_f32 v172, v210, v211
	v_cvt_pk_bf16_f32 v173, v212, v213
	v_cvt_pk_bf16_f32 v174, v222, v220
	v_cvt_pk_bf16_f32 v175, v221, v223
	ds_read_b64_tr_b16 v[208:209], v186 offset:0
	ds_read_b64_tr_b16 v[210:211], v186 offset:2048
	ds_read_b64_tr_b16 v[212:213], v186 offset:4096
	ds_read_b64_tr_b16 v[214:215], v186 offset:6144
	ds_read_b64_tr_b16 v[218:219], v186 offset:8192
	ds_read_b64_tr_b16 v[220:221], v186 offset:10240
	ds_read_b64_tr_b16 v[222:223], v186 offset:12288
	ds_read_b64_tr_b16 v[224:225], v186 offset:14336
	v_permlane32_swap_b32_e32 v205, v206
	v_permlane32_swap_b32_e32 v160, v162
	v_permlane32_swap_b32_e32 v161, v163
	v_permlane32_swap_b32_e32 v164, v166
	v_permlane32_swap_b32_e32 v165, v167
	v_permlane32_swap_b32_e32 v168, v170
	v_permlane32_swap_b32_e32 v169, v171
	v_permlane32_swap_b32_e32 v172, v174
	v_permlane32_swap_b32_e32 v173, v175
	s_cmp_gt_u32 s9, 64
	s_cselect_b64 s[4:5], -1, 0
	s_and_b64 vcc, exec, s[4:5]
	s_cbranch_vccnz .LBB0_1535
; #define SBAR() __builtin_amdgcn_sched_barrier(0)
; #define SLOAD(i, k0) do { sr_[i].vs0 = St::ld8(&Vh[(long)((k0) + sr) * LDK + sc]); sr_[i].vs1 = St::ld8(&Vh[(long)((k0) + 32 + sr) * LDK + sc]); \
;     sr_[i].ks0 = St::ld8(&Kh[(long)((k0) + sr) * LDK + sc]); sr_[i].ks1 = St::ld8(&Kh[(long)((k0) + 32 + sr) * LDK + sc]); } while (0)
; #define SWAIT() do { if constexpr (SDEPTH == 2) asm volatile("s_waitcnt vmcnt(4)" ::: "memory"); else asm volatile("s_waitcnt vmcnt(0)" ::: "memory"); } while (0)
; #define RESC(a) do { if (__any((a) < 1.f)) { if (hi == 0) al_l[r32] = (a); asm volatile("s_waitcnt lgkmcnt(0)" ::: "memory"); \
;     for (int d = 0; d < 4; ++d) for (int r = 0; r < 16; ++r) o[d][r] *= al_l[crow(r, hi)]; } } while (0)
; template <typename TQ>
; __device__ __forceinline__ void attn_dense_body(const TQ* __restrict__ Qb, const bf16* __restrict__ Kh, const bf16* __restrict__ Vh,
;                                                 bf16* __restrict__ Ob, int seq, char* lds, const int tid) {
;     ...
;     if (SDEPTH == 1 || j + 3 < NT) SLOAD(SE, (j + 1 + SDEPTH) * KVBLK); SBAR();
;     pv_d0(o, vb0 + (int)SHM_V, pa0, pa1, pa2, pa3); partialSM(pA0, pA1, m_reg, mnA, alA);
;     __syncthreads(); SWAIT(); SWRITE(1, SO);
;     RESC(alA); __syncthreads();
	v_add_co_u32_e32 v128, vcc, 0xffffe000, v178
	s_nop 1
	v_addc_co_u32_e32 v129, vcc, -1, v179, vcc
	v_add_co_u32_e32 v132, vcc, 0xe53fe000, v178
	s_nop 1
	v_addc_co_u32_e32 v133, vcc, -1, v179, vcc
	v_add_co_u32_e32 v140, vcc, 0xe5400000, v178
	global_load_dwordx4 v[128:131], v[128:129], off
	s_nop 0
	global_load_dwordx4 v[132:135], v[132:133], off
	v_addc_co_u32_e32 v141, vcc, -1, v179, vcc
	global_load_dwordx4 v[136:139], v[178:179], off
	s_nop 0
	global_load_dwordx4 v[140:143], v[140:141], off
.LBB0_1535:
	s_waitcnt lgkmcnt(7)
	ds_read_b64_tr_b16 v[230:231], v186 offset:512
	ds_read_b64_tr_b16 v[232:233], v186 offset:2560
	ds_read_b64_tr_b16 v[234:235], v186 offset:4608
	ds_read_b64_tr_b16 v[236:237], v186 offset:6656
	ds_read_b64_tr_b16 v[238:239], v186 offset:8704
	ds_read_b64_tr_b16 v[240:241], v186 offset:10752
	ds_read_b64_tr_b16 v[242:243], v186 offset:12800
	ds_read_b64_tr_b16 v[244:245], v186 offset:14848
	s_waitcnt lgkmcnt(8)
	s_nop 0
	v_mfma_f32_32x32x16_bf16 v[0:15], v[160:163], v[208:211], v[0:15]
	ds_read_b64_tr_b16 v[208:209], v186 offset:1024
	ds_read_b64_tr_b16 v[210:211], v186 offset:3072
	v_mfma_f32_32x32x16_bf16 v[0:15], v[164:167], v[212:215], v[0:15]
	ds_read_b64_tr_b16 v[212:213], v186 offset:5120
	ds_read_b64_tr_b16 v[214:215], v186 offset:7168
	v_mfma_f32_32x32x16_bf16 v[0:15], v[168:171], v[218:221], v[0:15]
	ds_read_b64_tr_b16 v[218:219], v186 offset:9216
	ds_read_b64_tr_b16 v[220:221], v186 offset:11264
	v_mfma_f32_32x32x16_bf16 v[0:15], v[172:175], v[222:225], v[0:15]
	s_waitcnt lgkmcnt(13)
	ds_read_b64_tr_b16 v[222:223], v186 offset:13312
	ds_read_b64_tr_b16 v[224:225], v186 offset:15360
	s_waitcnt lgkmcnt(8)
	v_mfma_f32_32x32x16_bf16 v[48:63], v[160:163], v[230:233], v[48:63]
	ds_read_b64_tr_b16 v[230:231], v186 offset:1536
	ds_read_b64_tr_b16 v[232:233], v186 offset:3584
	v_mfma_f32_32x32x16_bf16 v[48:63], v[164:167], v[234:237], v[48:63]
	ds_read_b64_tr_b16 v[234:235], v186 offset:5632
	ds_read_b64_tr_b16 v[236:237], v186 offset:7680
	v_mfma_f32_32x32x16_bf16 v[48:63], v[168:171], v[238:241], v[48:63]
	ds_read_b64_tr_b16 v[238:239], v186 offset:9728
	ds_read_b64_tr_b16 v[240:241], v186 offset:11776
	v_mfma_f32_32x32x16_bf16 v[48:63], v[172:175], v[242:245], v[48:63]
	s_waitcnt lgkmcnt(13)
	ds_read_b64_tr_b16 v[242:243], v186 offset:13824
	ds_read_b64_tr_b16 v[244:245], v186 offset:15872
	s_waitcnt lgkmcnt(8)
	v_mfma_f32_32x32x16_bf16 v[32:47], v[160:163], v[208:211], v[32:47]
	v_mfma_f32_32x32x16_bf16 v[32:47], v[164:167], v[212:215], v[32:47]
	v_mfma_f32_32x32x16_bf16 v[32:47], v[168:171], v[218:221], v[32:47]
	v_mfma_f32_32x32x16_bf16 v[32:47], v[172:175], v[222:225], v[32:47]
	s_waitcnt lgkmcnt(0)
	v_mfma_f32_32x32x16_bf16 v[16:31], v[160:163], v[230:233], v[16:31]
	v_max_f32_e32 v160, v81, v81
	v_max_f32_e32 v161, v80, v80
	v_max_f32_e32 v160, v161, v160
	v_max3_f32 v160, v160, v82, v83
	v_max3_f32 v160, v160, v84, v85
	v_max3_f32 v160, v160, v86, v87
	v_max3_f32 v160, v160, v88, v89
	v_max3_f32 v160, v160, v90, v91
	v_max3_f32 v160, v160, v92, v93
	v_mfma_f32_32x32x16_bf16 v[16:31], v[164:167], v[234:237], v[16:31]
	v_max3_f32 v160, v160, v94, v95
	v_max3_f32 v160, v160, v64, v65
	v_max3_f32 v160, v160, v66, v67
	v_max3_f32 v160, v160, v68, v69
	v_max3_f32 v160, v160, v70, v71
	v_max3_f32 v160, v160, v72, v73
	v_max3_f32 v160, v160, v74, v75
	v_max3_f32 v160, v160, v76, v77
	v_mfma_f32_32x32x16_bf16 v[16:31], v[168:171], v[238:241], v[16:31]
	v_max3_f32 v160, v160, v78, v79
	v_mov_b32_e32 v161, v160
	s_nop 1
	v_permlane32_swap_b32_e32 v160, v161
	v_max_f32_e32 v161, v161, v161
	v_max_f32_e32 v160, v160, v160
	v_max_f32_e32 v160, v160, v161
	v_sub_f32_e32 v161, v160, v204
	v_cmp_ge_f32_e32 vcc, s14, v161
	v_max_f32_e32 v161, v204, v204
	v_max_f32_e32 v161, v161, v160
	v_mfma_f32_32x32x16_bf16 v[16:31], v[172:175], v[242:245], v[16:31]
	v_sub_f32_e32 v160, v204, v161
	v_mul_f32_e32 v160, 0x3e0293ee, v160
	v_exp_f32_e32 v160, v160
	s_cmp_eq_u64 vcc, exec
	s_cselect_b64 s[38:39], -1, 0
	s_barrier
	s_waitcnt vmcnt(4)
	v_cndmask_b32_e64 v160, v160, 1.0, s[38:39]
	v_cmp_gt_f32_e32 vcc, 1.0, v160
	s_cmp_gt_u32 s9, 64
	s_cbranch_scc0 .Latt_stage_b
	s_waitcnt vmcnt(0)
.Latt_stage_b:
	ds_write_b128 v188, v[144:147] offset:16384
	ds_write_b128 v189, v[148:151] offset:16384
	ds_write_b128 v190, v[152:155] offset:49152
	ds_write_b128 v191, v[156:159] offset:49152
	s_cbranch_vccz .LBB0_1539
	s_and_saveexec_b64 s[6:7], s[36:37]
	ds_write_b32 v184, v160 offset:128
	s_or_b64 exec, exec, s[6:7]
	s_waitcnt lgkmcnt(0)
	v_add_u32_e32 v156, s8, v176
	ds_read_b128 v[144:147], v156 offset:224
	ds_read_b128 v[148:151], v156 offset:192
	ds_read_b128 v[152:155], v156 offset:160
	ds_read_b128 v[156:159], v156 offset:128
	s_waitcnt lgkmcnt(3)
	v_pk_mul_f32 v[12:13], v[12:13], v[144:145]
	s_waitcnt lgkmcnt(2)
	v_pk_mul_f32 v[8:9], v[8:9], v[148:149]
	s_waitcnt lgkmcnt(1)
	v_pk_mul_f32 v[4:5], v[4:5], v[152:153]
	v_pk_mul_f32 v[14:15], v[14:15], v[146:147]
	v_pk_mul_f32 v[10:11], v[10:11], v[150:151]
	v_pk_mul_f32 v[6:7], v[6:7], v[154:155]
	s_waitcnt lgkmcnt(0)
	v_pk_mul_f32 v[2:3], v[2:3], v[158:159]
	v_pk_mul_f32 v[0:1], v[0:1], v[156:157]
	v_pk_mul_f32 v[60:61], v[60:61], v[144:145]
	v_pk_mul_f32 v[56:57], v[56:57], v[148:149]
	v_pk_mul_f32 v[52:53], v[52:53], v[152:153]
	v_pk_mul_f32 v[62:63], v[62:63], v[146:147]
	v_pk_mul_f32 v[58:59], v[58:59], v[150:151]
	v_pk_mul_f32 v[54:55], v[54:55], v[154:155]
	v_pk_mul_f32 v[50:51], v[50:51], v[158:159]
	v_pk_mul_f32 v[48:49], v[48:49], v[156:157]
	v_pk_mul_f32 v[44:45], v[44:45], v[144:145]
	v_pk_mul_f32 v[40:41], v[40:41], v[148:149]
	v_pk_mul_f32 v[36:37], v[36:37], v[152:153]
	v_pk_mul_f32 v[46:47], v[46:47], v[146:147]
	v_pk_mul_f32 v[42:43], v[42:43], v[150:151]
	v_pk_mul_f32 v[38:39], v[38:39], v[154:155]
	v_pk_mul_f32 v[34:35], v[34:35], v[158:159]
	v_pk_mul_f32 v[32:33], v[32:33], v[156:157]
	v_pk_mul_f32 v[28:29], v[28:29], v[144:145]
	v_pk_mul_f32 v[24:25], v[24:25], v[148:149]
	v_pk_mul_f32 v[20:21], v[20:21], v[152:153]
	v_pk_mul_f32 v[30:31], v[30:31], v[146:147]
	v_pk_mul_f32 v[26:27], v[26:27], v[150:151]
	v_pk_mul_f32 v[22:23], v[22:23], v[154:155]
	v_pk_mul_f32 v[18:19], v[18:19], v[158:159]
	v_pk_mul_f32 v[16:17], v[16:17], v[156:157]

; __global__ void __launch_bounds__(512, 2) fwd_kernel(Params p) {
	.amdhsa_kernel _Z10fwd_kernel6Params
		.amdhsa_group_segment_fixed_size 0
		.amdhsa_private_segment_fixed_size 0
		.amdhsa_kernarg_size 440
		.amdhsa_user_sgpr_count 2
		.amdhsa_user_sgpr_dispatch_ptr 0
		.amdhsa_user_sgpr_queue_ptr 0
		.amdhsa_user_sgpr_kernarg_segment_ptr 1
		.amdhsa_user_sgpr_dispatch_id 0
		.amdhsa_user_sgpr_kernarg_preload_length 0
		.amdhsa_user_sgpr_kernarg_preload_offset 0
		.amdhsa_user_sgpr_private_segment_size 0
		.amdhsa_uses_dynamic_stack 0
		.amdhsa_enable_private_segment 0
		.amdhsa_system_sgpr_workgroup_id_x 1
		.amdhsa_system_sgpr_workgroup_id_y 0
		.amdhsa_system_sgpr_workgroup_id_z 0
		.amdhsa_system_sgpr_workgroup_info 0
		.amdhsa_system_vgpr_workitem_id 2
		.amdhsa_next_free_vgpr 256
		.amdhsa_next_free_sgpr 98
		.amdhsa_accum_offset 256
		.amdhsa_reserve_vcc 1
		.amdhsa_float_round_mode_32 0
		.amdhsa_float_round_mode_16_64 0
		.amdhsa_float_denorm_mode_32 3
		.amdhsa_float_denorm_mode_16_64 3
		.amdhsa_dx10_clamp 1
		.amdhsa_ieee_mode 1
		.amdhsa_fp16_overflow 0
		.amdhsa_tg_split 0
		.amdhsa_exception_fp_ieee_invalid_op 0
		.amdhsa_exception_fp_denorm_src 0
		.amdhsa_exception_fp_ieee_div_zero 0
		.amdhsa_exception_fp_ieee_overflow 0
		.amdhsa_exception_fp_ieee_underflow 0
		.amdhsa_exception_fp_ieee_inexact 0
		.amdhsa_exception_int_div_zero 0
	.end_amdhsa_kernel

; __global__ void __launch_bounds__(512, 2) fwd_kernel(Params p) {
amdhsa.kernels:
  - .agpr_count:     0
    .args:
      - .offset:         0
        .size:           184
        .value_kind:     by_value
      - .offset:         184
        .size:           4
        .value_kind:     hidden_block_count_x
      - .offset:         188
        .size:           4
        .value_kind:     hidden_block_count_y
      - .offset:         192
        .size:           4
        .value_kind:     hidden_block_count_z
      - .offset:         196
        .size:           2
        .value_kind:     hidden_group_size_x
      - .offset:         198
        .size:           2
        .value_kind:     hidden_group_size_y
      - .offset:         200
        .size:           2
        .value_kind:     hidden_group_size_z
      - .offset:         202
        .size:           2
        .value_kind:     hidden_remainder_x
      - .offset:         204
        .size:           2
        .value_kind:     hidden_remainder_y
      - .offset:         206
        .size:           2
        .value_kind:     hidden_remainder_z
      - .offset:         224
        .size:           8
        .value_kind:     hidden_global_offset_x
      - .offset:         232
        .size:           8
        .value_kind:     hidden_global_offset_y
      - .offset:         240
        .size:           8
        .value_kind:     hidden_global_offset_z
      - .offset:         248
        .size:           2
        .value_kind:     hidden_grid_dims
      - .offset:         272
        .size:           8
        .value_kind:     hidden_multigrid_sync_arg
      - .offset:         304
        .size:           4
        .value_kind:     hidden_dynamic_lds_size
    .group_segment_fixed_size: 0
    .kernarg_segment_align: 8
    .kernarg_segment_size: 440
    .language:       OpenCL C
    .language_version:
      - 2
      - 0
    .max_flat_workgroup_size: 512
    .name:           _Z10fwd_kernel6Params
    .private_segment_fixed_size: 0
    .sgpr_count:     104
    .sgpr_spill_count: 179
    .symbol:         _Z10fwd_kernel6Params.kd
    .uniform_work_group_size: 1
    .uses_dynamic_stack: false
    .vgpr_count:     256
    .vgpr_spill_count: 0
    .wavefront_size: 64
